# v086 + RG-LRU scan v5: serial scan only updates h and parks it (f32) in the consumed LA/BT rows; y=bf16(h*g) computed by all 512 threads in the Y-store block (scan 8 -> 6 instrs per step)
# baseline (speedup 1.0000x reference)
; #define LAS __attribute__((address_space(3)))
; DI unsigned pk2(float a, float b) { f32x2 v = {a, b}; bf2_t r = __builtin_convertvector(v, bf2_t); return __builtin_bit_cast(unsigned, r); }
; DI void phase_rglru(const Params& p, unsigned char* shm) {
;     ...
;                     hst = (hst - om * hst) + bt;
;                     *(LAS bf16_t*)(lds + GT + r * TR + tid * 2) = (bf16_t)(pk2(hst * g, 0.f) & 0xffffu);
;     ...
;             const size_t ob = base + (size_t)tile * 64 * 1536;
; #pragma unroll
;             for (int j = 0; j < 3; ++j) *(u32x4*)(Y + ob + goff[j]) = *(const LAS u32x4*)(lds + GT + loff[j]);
.LBB0_842:
	s_or_b64 exec, exec, s[2:3]
	s_waitcnt lgkmcnt(0)
	s_barrier
	s_lshl_b64 s[2:3], s[10:11], 1
	s_add_u32 s2, s62, s2
	s_addc_u32 s3, s63, s3
	s_add_i32 s64, s64, 1
	v_mul_hi_i32 v148, v192, s71
	v_ashrrev_i32_e32 v148, 2, v148
	v_mul_u32_u24_e32 v149, 24, v148
	v_sub_u32_e32 v150, v192, v149
	v_mul_u32_u24_e32 v151, 0x190, v148
	v_lshl_add_u32 v170, v150, 4, v151
	v_lshrrev_b32_e32 v149, 3, v150
	v_lshl_add_u32 v151, v149, 7, v151
	v_and_b32_e32 v149, 3, v150
	v_lshl_add_u32 v151, v149, 5, v151
	v_and_b32_e32 v149, 4, v150
	v_mul_u32_u24_e32 v149, 0x1900, v149
	v_add_u32_e32 v151, v151, v149
	v_add_u32_e32 v151, 0x13100, v151
	v_mul_u32_u24_e32 v120, 0xc00, v148
	v_lshl_add_u32 v120, v150, 4, v120
	ds_read_b128 v[124:127], v151
	ds_read_b128 v[128:131], v151 offset:16
	ds_read_b128 v[132:135], v170 offset:52480
	v_add_u32_e32 v171, 0x200, v192
	v_mul_hi_i32 v148, v171, s71
	v_ashrrev_i32_e32 v148, 2, v148
	v_mul_u32_u24_e32 v149, 24, v148
	v_sub_u32_e32 v150, v171, v149
	v_mul_u32_u24_e32 v151, 0x190, v148
	v_lshl_add_u32 v170, v150, 4, v151
	v_lshrrev_b32_e32 v149, 3, v150
	v_lshl_add_u32 v151, v149, 7, v151
	v_and_b32_e32 v149, 3, v150
	v_lshl_add_u32 v151, v149, 5, v151
	v_and_b32_e32 v149, 4, v150
	v_mul_u32_u24_e32 v149, 0x1900, v149
	v_add_u32_e32 v151, v151, v149
	v_add_u32_e32 v151, 0x13100, v151
	v_mul_u32_u24_e32 v121, 0xc00, v148
	v_lshl_add_u32 v121, v150, 4, v121
	ds_read_b128 v[136:139], v151
	ds_read_b128 v[140:143], v151 offset:16
	ds_read_b128 v[144:147], v170 offset:52480
	v_add_u32_e32 v171, 0x400, v192
	v_mul_hi_i32 v148, v171, s71
	v_ashrrev_i32_e32 v148, 2, v148
	v_mul_u32_u24_e32 v149, 24, v148
	v_sub_u32_e32 v150, v171, v149
	v_mul_u32_u24_e32 v151, 0x190, v148
	v_lshl_add_u32 v170, v150, 4, v151
	v_lshrrev_b32_e32 v149, 3, v150
	v_lshl_add_u32 v151, v149, 7, v151
	v_and_b32_e32 v149, 3, v150
	v_lshl_add_u32 v151, v149, 5, v151
	v_and_b32_e32 v149, 4, v150
	v_mul_u32_u24_e32 v149, 0x1900, v149
	v_add_u32_e32 v151, v151, v149
	v_add_u32_e32 v151, 0x13100, v151
	v_mul_u32_u24_e32 v122, 0xc00, v148
	v_lshl_add_u32 v122, v150, 4, v122
	ds_read_b128 v[210:213], v151
	ds_read_b128 v[214:217], v151 offset:16
	ds_read_b128 v[218:221], v170 offset:52480
	s_waitcnt lgkmcnt(6)
	v_lshlrev_b32_e32 v222, 16, v132
	v_and_b32_e32 v223, 0xffff0000, v132
	v_pk_mul_f32 v[124:125], v[124:125], v[222:223]
	v_lshlrev_b32_e32 v222, 16, v133
	v_and_b32_e32 v223, 0xffff0000, v133
	v_pk_mul_f32 v[126:127], v[126:127], v[222:223]
	v_lshlrev_b32_e32 v222, 16, v134
	v_and_b32_e32 v223, 0xffff0000, v134
	v_pk_mul_f32 v[128:129], v[128:129], v[222:223]
	v_lshlrev_b32_e32 v222, 16, v135
	v_and_b32_e32 v223, 0xffff0000, v135
	v_pk_mul_f32 v[130:131], v[130:131], v[222:223]
	v_cvt_pk_bf16_f32 v124, v124, v125
	v_cvt_pk_bf16_f32 v125, v126, v127
	v_cvt_pk_bf16_f32 v126, v128, v129
	v_cvt_pk_bf16_f32 v127, v130, v131
	global_store_dwordx4 v120, v[124:127], s[2:3]
	s_waitcnt lgkmcnt(3)
	v_lshlrev_b32_e32 v222, 16, v144
	v_and_b32_e32 v223, 0xffff0000, v144
	v_pk_mul_f32 v[136:137], v[136:137], v[222:223]
	v_lshlrev_b32_e32 v222, 16, v145
	v_and_b32_e32 v223, 0xffff0000, v145
	v_pk_mul_f32 v[138:139], v[138:139], v[222:223]
	v_lshlrev_b32_e32 v222, 16, v146
	v_and_b32_e32 v223, 0xffff0000, v146
	v_pk_mul_f32 v[140:141], v[140:141], v[222:223]
	v_lshlrev_b32_e32 v222, 16, v147
	v_and_b32_e32 v223, 0xffff0000, v147
	v_pk_mul_f32 v[142:143], v[142:143], v[222:223]
	v_cvt_pk_bf16_f32 v136, v136, v137
	v_cvt_pk_bf16_f32 v137, v138, v139
	v_cvt_pk_bf16_f32 v138, v140, v141
	v_cvt_pk_bf16_f32 v139, v142, v143
	global_store_dwordx4 v121, v[136:139], s[2:3]
	s_waitcnt lgkmcnt(0)
	v_lshlrev_b32_e32 v222, 16, v218
	v_and_b32_e32 v223, 0xffff0000, v218
	v_pk_mul_f32 v[210:211], v[210:211], v[222:223]
	v_lshlrev_b32_e32 v222, 16, v219
	v_and_b32_e32 v223, 0xffff0000, v219
	v_pk_mul_f32 v[212:213], v[212:213], v[222:223]
	v_lshlrev_b32_e32 v222, 16, v220
	v_and_b32_e32 v223, 0xffff0000, v220
	v_pk_mul_f32 v[214:215], v[214:215], v[222:223]
	v_lshlrev_b32_e32 v222, 16, v221
	v_and_b32_e32 v223, 0xffff0000, v221
	v_pk_mul_f32 v[216:217], v[216:217], v[222:223]
	v_cvt_pk_bf16_f32 v210, v210, v211
	v_cvt_pk_bf16_f32 v211, v212, v213
	v_cvt_pk_bf16_f32 v212, v214, v215
	v_cvt_pk_bf16_f32 v213, v216, v217
	global_store_dwordx4 v122, v[210:213], s[2:3]

; #define LAS __attribute__((address_space(3)))
; DI unsigned pk2(float a, float b) { f32x2 v = {a, b}; bf2_t r = __builtin_convertvector(v, bf2_t); return __builtin_bit_cast(unsigned, r); }
; DI void phase_rglru(const Params& p, unsigned char* shm) {
;     ...
;             if (tid < 192) {
; #pragma unroll 8
;                 for (int r = 0; r < 64; ++r) {
;                     const float om = __uint_as_float((unsigned)*(const LAS bf16_t*)(lds + LAo + r * TR + tid * 2) << 16);
;                     const float bt = __uint_as_float((unsigned)*(const LAS bf16_t*)(lds + BTo + r * TR + tid * 2) << 16);
;                     const float g = __uint_as_float((unsigned)*(const LAS bf16_t*)(lds + GT + r * TR + tid * 2) << 16);
;                     hst = (hst - om * hst) + bt;
;                     *(LAS bf16_t*)(lds + GT + r * TR + tid * 2) = (bf16_t)(pk2(hst * g, 0.f) & 0xffffu);
;                 }
.LBB0_851:
	s_andn2_saveexec_b64 s[2:3], s[2:3]
	s_cbranch_execz .LBB0_842
	v_mov_b32_e32 v126, 0
	v_mov_b32_e32 v127, 0
	v_mov_b32_e32 v128, 0
	v_mov_b32_e32 v129, 0
	v_mov_b32_e32 v130, 0
	v_mov_b32_e32 v131, 0
	v_mov_b32_e32 v132, 0
	v_mov_b32_e32 v133, 0
	v_mov_b32_e32 v134, 0
	v_mov_b32_e32 v135, 0
	v_mov_b32_e32 v136, 0
	v_mov_b32_e32 v137, 0
	v_mov_b32_e32 v138, 0
	v_mov_b32_e32 v139, 0
	v_mov_b32_e32 v140, 0
	v_mov_b32_e32 v141, 0
	v_add_u32_e32 v121, 0x13100, v176
	v_add_u32_e32 v122, 0x19500, v176
	v_and_b32_e32 v124, 31, v192
	v_lshlrev_b32_e32 v124, 2, v124
	v_lshrrev_b32_e32 v125, 6, v192
	v_lshl_add_u32 v124, v125, 7, v124
	v_and_b32_e32 v125, 32, v192
	v_mul_u32_u24_e32 v125, 0x320, v125
	v_add_u32_e32 v124, v124, v125
	v_add_u32_e32 v124, 0x13100, v124
	ds_read_u16_d16_hi v126, v121
	ds_read_u16_d16_hi v134, v122
	ds_read_u16_d16_hi v127, v121 offset:400
	ds_read_u16_d16_hi v135, v122 offset:400
	ds_read_u16_d16_hi v128, v121 offset:800
	ds_read_u16_d16_hi v136, v122 offset:800
	ds_read_u16_d16_hi v129, v121 offset:1200
	ds_read_u16_d16_hi v137, v122 offset:1200
	ds_read_u16_d16_hi v130, v121 offset:1600
	ds_read_u16_d16_hi v138, v122 offset:1600
	s_waitcnt lgkmcnt(8)
	v_fma_f32 v150, -v152, v126, v152
	v_add_f32_e32 v152, v150, v134
	ds_write_b32 v124, v152
	ds_read_u16_d16_hi v131, v121 offset:2000
	ds_read_u16_d16_hi v139, v122 offset:2000
	s_waitcnt lgkmcnt(9)
	v_fma_f32 v150, -v152, v127, v152
	v_add_f32_e32 v152, v150, v135
	ds_write_b32 v124, v152 offset:400
	ds_read_u16_d16_hi v132, v121 offset:2400
	ds_read_u16_d16_hi v140, v122 offset:2400
	s_waitcnt lgkmcnt(10)
	v_fma_f32 v150, -v152, v128, v152
	v_add_f32_e32 v152, v150, v136
	ds_write_b32 v124, v152 offset:800
	ds_read_u16_d16_hi v133, v121 offset:2800
	ds_read_u16_d16_hi v141, v122 offset:2800
	s_waitcnt lgkmcnt(11)
	v_fma_f32 v150, -v152, v129, v152
	v_add_f32_e32 v152, v150, v137
	ds_write_b32 v124, v152 offset:1200
	ds_read_u16_d16_hi v126, v121 offset:3200
	ds_read_u16_d16_hi v134, v122 offset:3200
	s_waitcnt lgkmcnt(12)
	v_fma_f32 v150, -v152, v130, v152
	v_add_f32_e32 v152, v150, v138
	ds_write_b32 v124, v152 offset:1600
	ds_read_u16_d16_hi v127, v121 offset:3600
	ds_read_u16_d16_hi v135, v122 offset:3600
	s_waitcnt lgkmcnt(12)
	v_fma_f32 v150, -v152, v131, v152
	v_add_f32_e32 v152, v150, v139
	ds_write_b32 v124, v152 offset:2000
	ds_read_u16_d16_hi v128, v121 offset:4000
	ds_read_u16_d16_hi v136, v122 offset:4000
	s_waitcnt lgkmcnt(12)
	v_fma_f32 v150, -v152, v132, v152
	v_add_f32_e32 v152, v150, v140
	ds_write_b32 v124, v152 offset:2400
	ds_read_u16_d16_hi v129, v121 offset:4400
	ds_read_u16_d16_hi v137, v122 offset:4400
	s_waitcnt lgkmcnt(12)
	v_fma_f32 v150, -v152, v133, v152
	v_add_f32_e32 v152, v150, v141
	ds_write_b32 v124, v152 offset:2800
	ds_read_u16_d16_hi v130, v121 offset:4800
	ds_read_u16_d16_hi v138, v122 offset:4800
	s_waitcnt lgkmcnt(12)
	v_fma_f32 v150, -v152, v126, v152
	v_add_f32_e32 v152, v150, v134
	ds_write_b32 v124, v152 offset:3200
	ds_read_u16_d16_hi v131, v121 offset:5200
	ds_read_u16_d16_hi v139, v122 offset:5200
	s_waitcnt lgkmcnt(12)
	v_fma_f32 v150, -v152, v127, v152
	v_add_f32_e32 v152, v150, v135
	ds_write_b32 v124, v152 offset:3600
	ds_read_u16_d16_hi v132, v121 offset:5600
	ds_read_u16_d16_hi v140, v122 offset:5600
	s_waitcnt lgkmcnt(12)
	v_fma_f32 v150, -v152, v128, v152
	v_add_f32_e32 v152, v150, v136
	ds_write_b32 v124, v152 offset:4000
	ds_read_u16_d16_hi v133, v121 offset:6000
	ds_read_u16_d16_hi v141, v122 offset:6000
	s_waitcnt lgkmcnt(12)
	v_fma_f32 v150, -v152, v129, v152
	v_add_f32_e32 v152, v150, v137
	ds_write_b32 v124, v152 offset:4400
	ds_read_u16_d16_hi v126, v121 offset:6400
	ds_read_u16_d16_hi v134, v122 offset:6400
	s_waitcnt lgkmcnt(12)
	v_fma_f32 v150, -v152, v130, v152
	v_add_f32_e32 v152, v150, v138
	ds_write_b32 v124, v152 offset:4800
	ds_read_u16_d16_hi v127, v121 offset:6800
	ds_read_u16_d16_hi v135, v122 offset:6800
	s_waitcnt lgkmcnt(12)
	v_fma_f32 v150, -v152, v131, v152
	v_add_f32_e32 v152, v150, v139
	ds_write_b32 v124, v152 offset:5200
	ds_read_u16_d16_hi v128, v121 offset:7200
	ds_read_u16_d16_hi v136, v122 offset:7200
	s_waitcnt lgkmcnt(12)
	v_fma_f32 v150, -v152, v132, v152
	v_add_f32_e32 v152, v150, v140
	ds_write_b32 v124, v152 offset:5600
	ds_read_u16_d16_hi v129, v121 offset:7600
	ds_read_u16_d16_hi v137, v122 offset:7600
	s_waitcnt lgkmcnt(12)
	v_fma_f32 v150, -v152, v133, v152
	v_add_f32_e32 v152, v150, v141
	ds_write_b32 v124, v152 offset:6000
	ds_read_u16_d16_hi v130, v121 offset:8000
	ds_read_u16_d16_hi v138, v122 offset:8000
	s_waitcnt lgkmcnt(12)
	v_fma_f32 v150, -v152, v126, v152
	v_add_f32_e32 v152, v150, v134
	ds_write_b32 v124, v152 offset:6400
	ds_read_u16_d16_hi v131, v121 offset:8400
	ds_read_u16_d16_hi v139, v122 offset:8400
	s_waitcnt lgkmcnt(12)
	v_fma_f32 v150, -v152, v127, v152
	v_add_f32_e32 v152, v150, v135
	ds_write_b32 v124, v152 offset:6800
	ds_read_u16_d16_hi v132, v121 offset:8800
	ds_read_u16_d16_hi v140, v122 offset:8800
	s_waitcnt lgkmcnt(12)
	v_fma_f32 v150, -v152, v128, v152
	v_add_f32_e32 v152, v150, v136
	ds_write_b32 v124, v152 offset:7200
	ds_read_u16_d16_hi v133, v121 offset:9200
	ds_read_u16_d16_hi v141, v122 offset:9200
	s_waitcnt lgkmcnt(12)
	v_fma_f32 v150, -v152, v129, v152
	v_add_f32_e32 v152, v150, v137
	ds_write_b32 v124, v152 offset:7600
	ds_read_u16_d16_hi v126, v121 offset:9600
	ds_read_u16_d16_hi v134, v122 offset:9600
	s_waitcnt lgkmcnt(12)
	v_fma_f32 v150, -v152, v130, v152
	v_add_f32_e32 v152, v150, v138
	ds_write_b32 v124, v152 offset:8000
	ds_read_u16_d16_hi v127, v121 offset:10000
	ds_read_u16_d16_hi v135, v122 offset:10000
	s_waitcnt lgkmcnt(12)
; #define LAS __attribute__((address_space(3)))
; DI unsigned pk2(float a, float b) { f32x2 v = {a, b}; bf2_t r = __builtin_convertvector(v, bf2_t); return __builtin_bit_cast(unsigned, r); }
; DI void phase_rglru(const Params& p, unsigned char* shm) {
;     ...
;             if (tid < 192) {
; #pragma unroll 8
;                 for (int r = 0; r < 64; ++r) {
;                     const float om = __uint_as_float((unsigned)*(const LAS bf16_t*)(lds + LAo + r * TR + tid * 2) << 16);
;                     const float bt = __uint_as_float((unsigned)*(const LAS bf16_t*)(lds + BTo + r * TR + tid * 2) << 16);
;                     const float g = __uint_as_float((unsigned)*(const LAS bf16_t*)(lds + GT + r * TR + tid * 2) << 16);
;                     hst = (hst - om * hst) + bt;
;                     *(LAS bf16_t*)(lds + GT + r * TR + tid * 2) = (bf16_t)(pk2(hst * g, 0.f) & 0xffffu);
;                 }
	v_fma_f32 v150, -v152, v131, v152
	v_add_f32_e32 v152, v150, v139
	ds_write_b32 v124, v152 offset:8400
	ds_read_u16_d16_hi v128, v121 offset:10400
	ds_read_u16_d16_hi v136, v122 offset:10400
	s_waitcnt lgkmcnt(12)
	v_fma_f32 v150, -v152, v132, v152
	v_add_f32_e32 v152, v150, v140
	ds_write_b32 v124, v152 offset:8800
	ds_read_u16_d16_hi v129, v121 offset:10800
	ds_read_u16_d16_hi v137, v122 offset:10800
	s_waitcnt lgkmcnt(12)
	v_fma_f32 v150, -v152, v133, v152
	v_add_f32_e32 v152, v150, v141
	ds_write_b32 v124, v152 offset:9200
	ds_read_u16_d16_hi v130, v121 offset:11200
	ds_read_u16_d16_hi v138, v122 offset:11200
	s_waitcnt lgkmcnt(12)
	v_fma_f32 v150, -v152, v126, v152
	v_add_f32_e32 v152, v150, v134
	ds_write_b32 v124, v152 offset:9600
	ds_read_u16_d16_hi v131, v121 offset:11600
	ds_read_u16_d16_hi v139, v122 offset:11600
	s_waitcnt lgkmcnt(12)
	v_fma_f32 v150, -v152, v127, v152
	v_add_f32_e32 v152, v150, v135
	ds_write_b32 v124, v152 offset:10000
	ds_read_u16_d16_hi v132, v121 offset:12000
	ds_read_u16_d16_hi v140, v122 offset:12000
	s_waitcnt lgkmcnt(12)
	v_fma_f32 v150, -v152, v128, v152
	v_add_f32_e32 v152, v150, v136
	ds_write_b32 v124, v152 offset:10400
	ds_read_u16_d16_hi v133, v121 offset:12400
	ds_read_u16_d16_hi v141, v122 offset:12400
	s_waitcnt lgkmcnt(12)
	v_fma_f32 v150, -v152, v129, v152
	v_add_f32_e32 v152, v150, v137
	ds_write_b32 v124, v152 offset:10800
	ds_read_u16_d16_hi v126, v121 offset:12800
	ds_read_u16_d16_hi v134, v122 offset:12800
	s_waitcnt lgkmcnt(12)
	v_fma_f32 v150, -v152, v130, v152
	v_add_f32_e32 v152, v150, v138
	ds_write_b32 v124, v152 offset:11200
	ds_read_u16_d16_hi v127, v121 offset:13200
	ds_read_u16_d16_hi v135, v122 offset:13200
	s_waitcnt lgkmcnt(12)
	v_fma_f32 v150, -v152, v131, v152
	v_add_f32_e32 v152, v150, v139
	ds_write_b32 v124, v152 offset:11600
	ds_read_u16_d16_hi v128, v121 offset:13600
	ds_read_u16_d16_hi v136, v122 offset:13600
	s_waitcnt lgkmcnt(12)
	v_fma_f32 v150, -v152, v132, v152
	v_add_f32_e32 v152, v150, v140
	ds_write_b32 v124, v152 offset:12000
	ds_read_u16_d16_hi v129, v121 offset:14000
	ds_read_u16_d16_hi v137, v122 offset:14000
	s_waitcnt lgkmcnt(12)
	v_fma_f32 v150, -v152, v133, v152
	v_add_f32_e32 v152, v150, v141
	ds_write_b32 v124, v152 offset:12400
	ds_read_u16_d16_hi v130, v121 offset:14400
	ds_read_u16_d16_hi v138, v122 offset:14400
	s_waitcnt lgkmcnt(12)
	v_fma_f32 v150, -v152, v126, v152
	v_add_f32_e32 v152, v150, v134
	ds_write_b32 v124, v152 offset:12800
	ds_read_u16_d16_hi v131, v121 offset:14800
	ds_read_u16_d16_hi v139, v122 offset:14800
	s_waitcnt lgkmcnt(12)
	v_fma_f32 v150, -v152, v127, v152
	v_add_f32_e32 v152, v150, v135
	ds_write_b32 v124, v152 offset:13200
	ds_read_u16_d16_hi v132, v121 offset:15200
	ds_read_u16_d16_hi v140, v122 offset:15200
	s_waitcnt lgkmcnt(12)
	v_fma_f32 v150, -v152, v128, v152
	v_add_f32_e32 v152, v150, v136
	ds_write_b32 v124, v152 offset:13600
	ds_read_u16_d16_hi v133, v121 offset:15600
	ds_read_u16_d16_hi v141, v122 offset:15600
	s_waitcnt lgkmcnt(12)
	v_fma_f32 v150, -v152, v129, v152
	v_add_f32_e32 v152, v150, v137
	ds_write_b32 v124, v152 offset:14000
	ds_read_u16_d16_hi v126, v121 offset:16000
	ds_read_u16_d16_hi v134, v122 offset:16000
	s_waitcnt lgkmcnt(12)
	v_fma_f32 v150, -v152, v130, v152
	v_add_f32_e32 v152, v150, v138
	ds_write_b32 v124, v152 offset:14400
	ds_read_u16_d16_hi v127, v121 offset:16400
	ds_read_u16_d16_hi v135, v122 offset:16400
	s_waitcnt lgkmcnt(12)
	v_fma_f32 v150, -v152, v131, v152
	v_add_f32_e32 v152, v150, v139
	ds_write_b32 v124, v152 offset:14800
	ds_read_u16_d16_hi v128, v121 offset:16800
	ds_read_u16_d16_hi v136, v122 offset:16800
	s_waitcnt lgkmcnt(12)
	v_fma_f32 v150, -v152, v132, v152
	v_add_f32_e32 v152, v150, v140
	ds_write_b32 v124, v152 offset:15200
	ds_read_u16_d16_hi v129, v121 offset:17200
	ds_read_u16_d16_hi v137, v122 offset:17200
	s_waitcnt lgkmcnt(12)
	v_fma_f32 v150, -v152, v133, v152
	v_add_f32_e32 v152, v150, v141
	ds_write_b32 v124, v152 offset:15600
	ds_read_u16_d16_hi v130, v121 offset:17600
	ds_read_u16_d16_hi v138, v122 offset:17600
	s_waitcnt lgkmcnt(12)
	v_fma_f32 v150, -v152, v126, v152
	v_add_f32_e32 v152, v150, v134
	ds_write_b32 v124, v152 offset:16000
	ds_read_u16_d16_hi v131, v121 offset:18000
	ds_read_u16_d16_hi v139, v122 offset:18000
	s_waitcnt lgkmcnt(12)
; #define LAS __attribute__((address_space(3)))
; DI unsigned pk2(float a, float b) { f32x2 v = {a, b}; bf2_t r = __builtin_convertvector(v, bf2_t); return __builtin_bit_cast(unsigned, r); }
; DI void phase_rglru(const Params& p, unsigned char* shm) {
;     ...
;             if (tid < 192) {
; #pragma unroll 8
;                 for (int r = 0; r < 64; ++r) {
;                     const float om = __uint_as_float((unsigned)*(const LAS bf16_t*)(lds + LAo + r * TR + tid * 2) << 16);
;                     const float bt = __uint_as_float((unsigned)*(const LAS bf16_t*)(lds + BTo + r * TR + tid * 2) << 16);
;                     const float g = __uint_as_float((unsigned)*(const LAS bf16_t*)(lds + GT + r * TR + tid * 2) << 16);
;                     hst = (hst - om * hst) + bt;
;                     *(LAS bf16_t*)(lds + GT + r * TR + tid * 2) = (bf16_t)(pk2(hst * g, 0.f) & 0xffffu);
;                 }
	v_fma_f32 v150, -v152, v127, v152
	v_add_f32_e32 v152, v150, v135
	ds_write_b32 v124, v152 offset:16400
	ds_read_u16_d16_hi v132, v121 offset:18400
	ds_read_u16_d16_hi v140, v122 offset:18400
	s_waitcnt lgkmcnt(12)
	v_fma_f32 v150, -v152, v128, v152
	v_add_f32_e32 v152, v150, v136
	ds_write_b32 v124, v152 offset:16800
	ds_read_u16_d16_hi v133, v121 offset:18800
	ds_read_u16_d16_hi v141, v122 offset:18800
	s_waitcnt lgkmcnt(12)
	v_fma_f32 v150, -v152, v129, v152
	v_add_f32_e32 v152, v150, v137
	ds_write_b32 v124, v152 offset:17200
	ds_read_u16_d16_hi v126, v121 offset:19200
	ds_read_u16_d16_hi v134, v122 offset:19200
	s_waitcnt lgkmcnt(12)
	v_fma_f32 v150, -v152, v130, v152
	v_add_f32_e32 v152, v150, v138
	ds_write_b32 v124, v152 offset:17600
	ds_read_u16_d16_hi v127, v121 offset:19600
	ds_read_u16_d16_hi v135, v122 offset:19600
	s_waitcnt lgkmcnt(12)
	v_fma_f32 v150, -v152, v131, v152
	v_add_f32_e32 v152, v150, v139
	ds_write_b32 v124, v152 offset:18000
	ds_read_u16_d16_hi v128, v121 offset:20000
	ds_read_u16_d16_hi v136, v122 offset:20000
	s_waitcnt lgkmcnt(12)
	v_fma_f32 v150, -v152, v132, v152
	v_add_f32_e32 v152, v150, v140
	ds_write_b32 v124, v152 offset:18400
	ds_read_u16_d16_hi v129, v121 offset:20400
	ds_read_u16_d16_hi v137, v122 offset:20400
	s_waitcnt lgkmcnt(12)
	v_fma_f32 v150, -v152, v133, v152
	v_add_f32_e32 v152, v150, v141
	ds_write_b32 v124, v152 offset:18800
	ds_read_u16_d16_hi v130, v121 offset:20800
	ds_read_u16_d16_hi v138, v122 offset:20800
	s_waitcnt lgkmcnt(12)
	v_fma_f32 v150, -v152, v126, v152
	v_add_f32_e32 v152, v150, v134
	ds_write_b32 v124, v152 offset:19200
	ds_read_u16_d16_hi v131, v121 offset:21200
	ds_read_u16_d16_hi v139, v122 offset:21200
	s_waitcnt lgkmcnt(12)
	v_fma_f32 v150, -v152, v127, v152
	v_add_f32_e32 v152, v150, v135
	ds_write_b32 v124, v152 offset:19600
	ds_read_u16_d16_hi v132, v121 offset:21600
	ds_read_u16_d16_hi v140, v122 offset:21600
	s_waitcnt lgkmcnt(12)
	v_fma_f32 v150, -v152, v128, v152
	v_add_f32_e32 v152, v150, v136
	ds_write_b32 v124, v152 offset:20000
	ds_read_u16_d16_hi v133, v121 offset:22000
	ds_read_u16_d16_hi v141, v122 offset:22000
	s_waitcnt lgkmcnt(12)
	v_fma_f32 v150, -v152, v129, v152
	v_add_f32_e32 v152, v150, v137
	ds_write_b32 v124, v152 offset:20400
	ds_read_u16_d16_hi v126, v121 offset:22400
	ds_read_u16_d16_hi v134, v122 offset:22400
	s_waitcnt lgkmcnt(12)
	v_fma_f32 v150, -v152, v130, v152
	v_add_f32_e32 v152, v150, v138
	ds_write_b32 v124, v152 offset:20800
	ds_read_u16_d16_hi v127, v121 offset:22800
	ds_read_u16_d16_hi v135, v122 offset:22800
	s_waitcnt lgkmcnt(12)
	v_fma_f32 v150, -v152, v131, v152
	v_add_f32_e32 v152, v150, v139
	ds_write_b32 v124, v152 offset:21200
	ds_read_u16_d16_hi v128, v121 offset:23200
	ds_read_u16_d16_hi v136, v122 offset:23200
	s_waitcnt lgkmcnt(12)
	v_fma_f32 v150, -v152, v132, v152
	v_add_f32_e32 v152, v150, v140
	ds_write_b32 v124, v152 offset:21600
	ds_read_u16_d16_hi v129, v121 offset:23600
	ds_read_u16_d16_hi v137, v122 offset:23600
	s_waitcnt lgkmcnt(12)
	v_fma_f32 v150, -v152, v133, v152
	v_add_f32_e32 v152, v150, v141
	ds_write_b32 v124, v152 offset:22000
	ds_read_u16_d16_hi v130, v121 offset:24000
	ds_read_u16_d16_hi v138, v122 offset:24000
	s_waitcnt lgkmcnt(12)
	v_fma_f32 v150, -v152, v126, v152
	v_add_f32_e32 v152, v150, v134
	ds_write_b32 v124, v152 offset:22400
	ds_read_u16_d16_hi v131, v121 offset:24400
	ds_read_u16_d16_hi v139, v122 offset:24400
	s_waitcnt lgkmcnt(12)
	v_fma_f32 v150, -v152, v127, v152
	v_add_f32_e32 v152, v150, v135
	ds_write_b32 v124, v152 offset:22800
	ds_read_u16_d16_hi v132, v121 offset:24800
	ds_read_u16_d16_hi v140, v122 offset:24800
	s_waitcnt lgkmcnt(12)
	v_fma_f32 v150, -v152, v128, v152
	v_add_f32_e32 v152, v150, v136
	ds_write_b32 v124, v152 offset:23200
	ds_read_u16_d16_hi v133, v121 offset:25200
	ds_read_u16_d16_hi v141, v122 offset:25200
	s_waitcnt lgkmcnt(12)
	v_fma_f32 v150, -v152, v129, v152
	v_add_f32_e32 v152, v150, v137
	ds_write_b32 v124, v152 offset:23600
	s_waitcnt lgkmcnt(10)
	v_fma_f32 v150, -v152, v130, v152
	v_add_f32_e32 v152, v150, v138
	ds_write_b32 v124, v152 offset:24000
	s_waitcnt lgkmcnt(8)
	v_fma_f32 v150, -v152, v131, v152
	v_add_f32_e32 v152, v150, v139
	ds_write_b32 v124, v152 offset:24400
	s_waitcnt lgkmcnt(6)
	v_fma_f32 v150, -v152, v132, v152
	v_add_f32_e32 v152, v150, v140
	ds_write_b32 v124, v152 offset:24800
	s_waitcnt lgkmcnt(4)
	v_fma_f32 v150, -v152, v133, v152
	v_add_f32_e32 v152, v150, v141
	ds_write_b32 v124, v152 offset:25200
	s_branch .LBB0_842
